# m2 phase: vt items only on the 160 workgroups that have two gmlp/ssd items (stride 1280 waves); the 64 workgroups with a third item get none
# speedup vs baseline: 1.0096x; 1.0002x over previous
.LBB0_443:
	s_or_b64 exec, exec, s[4:5]
	s_ashr_i32 s39, s73, 31
	s_lshr_b32 s2, s39, 29
	s_add_i32 s2, s73, s2
	s_ashr_i32 s10, s2, 3
	s_and_b32 s2, s2, -8
	s_sub_i32 s11, s73, s2
	s_ashr_i32 s2, s3, 31
	v_writelane_b32 v243, s2, 6
	s_lshl_b32 s2, s73, 6
	s_and_b32 s2, s2, 0x1c0
	v_writelane_b32 v243, s2, 7
	s_lshr_b32 s2, s3, 3
	s_cmp_gt_i32 s73, 31
	v_writelane_b32 v243, s2, 8
	s_cselect_b64 s[4:5], -1, 0
	s_sub_i32 s2, s73, 32
	v_writelane_b32 v243, s4, 9
	s_cmpk_lt_u32 s73, 0x220
	s_mov_b32 s49, 0
	v_writelane_b32 v243, s5, 10
	s_cselect_b64 s[4:5], -1, 0
	v_writelane_b32 v243, s4, 11
	s_mov_b32 s13, s49
	v_mbcnt_lo_u32_b32 v3, -1, 0
	v_writelane_b32 v243, s5, 12
	s_sub_i32 s4, s3, 32
	v_writelane_b32 v243, s4, 13
	v_writelane_b32 v243, s2, 14
	s_sub_i32 s2, s73, 0x60
	s_lshl_b32 s2, s2, 3
	s_cmp_lt_i32 s2, 0
	s_cselect_b32 s2, 0x800, s2
	v_writelane_b32 v243, s2, 15
	s_movk_i32 s2, 0x500
	v_writelane_b32 v243, s2, 16
	s_lshl_b32 s2, s11, 2
	s_lshl_b32 s4, s3, 9
	s_cmpk_lg_i32 s3, 0x100
	v_writelane_b32 v243, s4, 17
	s_cselect_b64 s[4:5], -1, 0
	v_writelane_b32 v243, s4, 18
	s_cmpk_lt_i32 s73, 0x200
	s_movk_i32 s79, 0xff00
	v_writelane_b32 v243, s5, 19
	s_cselect_b64 s[4:5], -1, 0
	v_writelane_b32 v243, s4, 20
	s_bfe_u32 s6, s73, 0x10001
	s_lshl_b32 s8, s6, 11
	v_writelane_b32 v243, s5, 21
	s_lshl_b32 s4, s73, 5
	v_writelane_b32 v243, s4, 22
	s_and_b32 s4, s4, 32
	s_add_i32 s87, s8, 0
	s_lshr_b32 s8, s73, 3
	s_add_i32 s4, s4, s8
	s_lshl_b32 s4, s4, 7
	v_writelane_b32 v243, s4, 23
	s_lshl_b32 s4, s6, 2
	s_bfe_u32 s5, s73, 0x10002
	v_writelane_b32 v243, s4, 24
	s_or_b32 s4, s4, 1
	s_lshl_b32 s7, s5, 1
	s_lshl_b32 s12, s5, 14
	s_lshl_b32 s5, s6, 8
	s_lshl_b32 s9, s4, 6
	v_writelane_b32 v243, s9, 25
	s_or_b32 s9, s5, 0x80
	v_writelane_b32 v243, s9, 26
	s_or_b32 s7, s7, s6
	v_writelane_b32 v243, s5, 27
	s_or_b32 s5, s5, 0xc0
	s_add_i32 s87, s87, 0x24000
	v_writelane_b32 v243, s5, 28
	s_lshl_b32 s5, s7, 20
	s_cmpk_lt_i32 s73, 0x100
	v_writelane_b32 v243, s5, 29
	s_cselect_b64 s[14:15], -1, 0
	v_writelane_b32 v243, s14, 30
	s_lshl_b32 s5, s11, 6
	s_mul_i32 s6, s6, 12
	v_writelane_b32 v243, s15, 31
	v_writelane_b32 v243, s12, 32
	s_lshl_b32 s14, s3, 4
	s_lshl_b32 s15, s7, 17
	v_writelane_b32 v243, s13, 33
	s_cmp_lt_i32 s11, 0
	s_mul_i32 s7, s11, 5
	v_writelane_b32 v243, s6, 34
	s_mul_i32 s4, s4, 3
	v_writelane_b32 v243, s4, 35
	s_mul_i32 s4, s11, 0x41
	s_cselect_b32 s2, s7, s2
	s_cselect_b32 s9, s4, s5
	s_add_i32 s7, s2, s10
	s_ashr_i32 s2, s7, 31
	s_lshr_b32 s4, s2, 29
	s_add_i32 s6, s7, s4
	s_ashr_i32 s4, s6, 3
	s_and_b32 s6, s6, 0x1f8
	s_sub_i32 s6, s7, s6
	s_mul_i32 s6, s6, 0x1800000
	s_lshr_b32 s2, s2, 28
	v_writelane_b32 v243, s6, 36
	s_ashr_i32 s6, s6, 31
	s_add_i32 s2, s7, s2
	v_writelane_b32 v243, s6, 37
	s_ashr_i32 s6, s2, 4
	v_writelane_b32 v243, s7, 38
	s_ashr_i32 s7, s6, 31
	s_lshl_b64 s[6:7], s[6:7], 20
	s_ashr_i32 s5, s4, 31
	v_writelane_b32 v243, s6, 39
	s_lshl_b64 s[4:5], s[4:5], 7
	s_add_i32 s2, s9, s10
	v_writelane_b32 v243, s7, 40
	v_writelane_b32 v243, s4, 41
	s_mov_b32 s38, 2
	s_movk_i32 s85, 0x200
	v_writelane_b32 v243, s5, 42
	s_ashr_i32 s4, s2, 31
	s_lshr_b32 s4, s4, 27
	s_add_i32 s4, s2, s4
	s_ashr_i32 s5, s4, 5
	s_and_b32 s4, s4, 0xffe0
	s_sub_i32 s4, s2, s4
	s_bfe_i32 s2, s4, 0x80000
	s_bfe_u32 s2, s2, 0x3000c
	s_add_i32 s6, s4, s2
	s_bfe_i32 s2, s6, 0x80000
	s_and_b32 s6, s6, 0xf8
	s_sub_i32 s4, s4, s6
	s_lshl_b32 s5, s5, 3
	s_sext_i32_i8 s4, s4
	v_writelane_b32 v243, s10, 43
	s_sext_i32_i16 s7, s2
	s_add_i32 s4, s5, s4
	s_lshr_b32 s2, s7, 3
	v_writelane_b32 v243, s4, 44
	s_ashr_i32 s4, s7, 3
	v_writelane_b32 v243, s4, 45
	s_bfe_i64 s[4:5], s[2:3], 0x100000
	v_writelane_b32 v243, s4, 46
	s_lshr_b32 s2, s11, 31
	v_mov_b32_e32 v11, 0
	v_writelane_b32 v243, s5, 47
	v_writelane_b32 v243, s11, 48
	v_writelane_b32 v243, s2, 49
	s_add_i32 s2, s73, 0xfffffee0
	v_writelane_b32 v243, s2, 50
	s_lshl_b32 s2, s73, 7
	v_writelane_b32 v243, s2, 51
	s_addk_i32 s2, 0xf000
	v_writelane_b32 v243, s2, 52
	s_lshl_b32 s2, s3, 7
	v_writelane_b32 v243, s2, 53
	s_addk_i32 s2, 0xf000
	v_writelane_b32 v243, s2, 54
	s_lshl_b32 s2, s3, 5
	s_bitcmp1_b32 s73, 0
	v_writelane_b32 v243, s2, 55
	s_cselect_b64 s[4:5], -1, 0
	v_writelane_b32 v243, s4, 56
	s_and_b32 s2, s73, 1
	s_lshl_b32 s2, s2, 12
	v_writelane_b32 v243, s5, 57
	s_lshl_b32 s4, s8, 7
	s_add_i32 s2, s2, s4
	s_add_i32 s4, s2, 0xfffffbf1
	v_writelane_b32 v243, s4, 58
	v_writelane_b32 v243, s15, 59
	s_or_b32 s4, s15, 0x15c80c00
	v_writelane_b32 v243, s4, 60
	s_or_b32 s4, s2, 15
	v_writelane_b32 v243, s4, 61
	s_sub_i32 s4, 0x3b71, s2
	s_sub_i32 s2, 0x3f8f, s2
	s_bitcmp1_b32 s3, 0
	v_writelane_b32 v243, s4, 62
	s_cselect_b64 s[4:5], -1, 0
	v_writelane_b32 v242, s4, 0
	v_writelane_b32 v243, s2, 63
	s_add_i32 s2, 0, 0x20400
	v_writelane_b32 v242, s5, 1
	v_writelane_b32 v242, s2, 2
	s_add_i32 s2, 0, 0x20c00
	v_writelane_b32 v242, s2, 3
	s_add_i32 s2, 0, 0x21800
	v_writelane_b32 v242, s2, 4
	s_add_i32 s2, 0, 0x22000
	v_writelane_b32 v242, s2, 5
	s_add_i32 s2, 0, 0x23000
	v_writelane_b32 v242, s2, 6
	s_add_i32 s2, 0, 0x11000
	v_writelane_b32 v242, s2, 7
	s_add_i32 s2, 0, 0x11008
	v_writelane_b32 v242, s2, 8
	v_cmp_ne_u32_e64 s[4:5], 0, v2
	s_mov_b32 s2, s14
	s_mov_b64 s[8:9], 0
	v_writelane_b32 v242, s4, 9
	s_ashr_i32 s15, s14, 31
	v_mov_b32_e32 v175, 0xe0000
	v_writelane_b32 v242, s5, 10
	v_writelane_b32 v242, s2, 11
	v_mov_b32_e32 v202, 0xe1000
	v_mov_b32_e32 v203, 0xffff
	v_writelane_b32 v242, s3, 12
	v_writelane_b32 v242, s8, 13
	s_mov_b32 s2, s76
	v_mov_b32_e32 v174, 0x3727c5ac
	v_writelane_b32 v242, s9, 14
	v_mov_b32_e32 v204, 1
	v_mov_b32_e32 v205, 0x7f800000
	v_mov_b32_e32 v206, 0x7fc00000
	v_mov_b32_e32 v207, 0xff800000
	v_mbcnt_hi_u32_b32 v208, -1, v3
	v_mov_b32_e32 v209, 0x1e000
	v_mov_b32_e32 v210, 0x24000
	v_mov_b32_e32 v211, 0x2a000
	v_mov_b32_e32 v212, 0x1800
	v_mov_b32_e32 v213, 0x60
	v_mov_b64_e32 v[176:177], 0x200
	v_mov_b64_e32 v[178:179], 0x1ff
	s_movk_i32 s33, 0x300
	s_movk_i32 s37, 0x1600
	s_movk_i32 s83, 0x60
	s_mov_b32 s89, 0xff800000
	s_movk_i32 s64, 0x1800
	s_movk_i32 s65, 0xffe0
	s_movk_i32 s42, 0xff
	s_mov_b32 s43, 0x5040100
	s_mov_b32 s52, 0x800000
	s_movk_i32 s53, 0x7f
	s_movk_i32 s36, 0xfbf
	s_mov_b32 s80, 0xfff80000
	s_movk_i32 s84, 0xfb
	s_movk_i32 s81, 0x108
	s_add_i32 s82, 0, 0x22800
	s_movk_i32 s78, 0xdf
	s_mov_b32 s7, 0
	s_lshl_b64 s[66:67], s[14:15], 12
	s_lshl_b64 s[68:69], s[14:15], 11
	s_mov_b64 s[4:5], -1
	s_mov_b64 s[74:75], 0x80
	s_mov_b32 s86, 0x3e000000
	s_mov_b32 s88, 0x3fb8aa3b
	s_mov_b64 s[94:95], 0x18000
	s_mov_b64 s[44:45], 0x80000
	s_mov_b64 s[56:57], 0x800
	s_mov_b64 s[58:59], 0x1000
	s_mov_b64 s[60:61], 0x30000
	s_mov_b32 s72, 0x3fb504f3
	v_writelane_b32 v242, s2, 15
	s_barrier
	s_nop 0
	v_writelane_b32 v242, s3, 16
	s_branch .LBB0_445
